# hyena: six x0 halo loads per unit no longer each followed by vmcnt(0); unpacked once before last inverse pass
# speedup vs baseline: 1.0113x; 1.0053x over previous
; __device__ __forceinline__ void conv8(const unsigned* zp, int cidx, float w0, float w1, float w2, float cb, float (&o)[8]) {
;     const u32x4 cur = *(const u32x4*)(zp + 4 * cidx); const unsigned prev = cidx > 0 ? zp[4 * cidx - 1] : 0u; const unsigned next = cidx < SEQ / 8 - 1 ? zp[4 * cidx + 4] : 0u;
; __device__ __forceinline__ void hyena_phase(LAS unsigned char* L, const Args& a, int vcu, int G) {
;     ...
;             const int r0a = ca, r0b = ca + 1;
;             const float wa0 = cw[r0a], wa1 = cw[3072 + r0a], wa2 = cw[6144 + r0a], c0a = cb[r0a];
;             const float wb0 = cw[r0b], wb1 = cw[3072 + r0b], wb2 = cw[6144 + r0b], c0b = cb[r0b];
;             const unsigned* p0a = (const unsigned*)(ZT + (size_t)r0a * ZLD + (size_t)b * SEQ); const unsigned* p0b = (const unsigned*)(ZT + (size_t)r0b * ZLD + (size_t)b * SEQ);
; #pragma unroll
;             for (int i = 0; i < 2; ++i) { const int cidx = tid + 512 * i; conv8(p0a, cidx, wa0, wa1, wa2, c0a, xa[i]); conv8(p0b, cidx, wb0, wb1, wb2, c0b, xb[i]); }
.LBB0_1045:
	s_waitcnt lgkmcnt(0)
	s_barrier
	global_load_dwordx2 v[64:65], v117, s[42:43]
	global_load_dwordx2 v[68:69], v153, s[42:43]
	global_load_dwordx2 v[66:67], v213, s[42:43]
	s_add_u32 s42, s68, s38
	s_addc_u32 s43, s69, s39
	global_load_dwordx2 v[70:71], v117, s[42:43]
	s_lshl_b64 s[42:43], s[40:41], 17
	s_add_u32 s21, s58, s42
	s_addc_u32 s23, s59, s43
	s_lshl_b32 s33, s96, 13
	s_and_b32 s33, s33, 0xe000
	s_lshl_b32 s73, s33, 1
	s_add_u32 s42, s21, s73
	s_addc_u32 s43, s23, 0
	global_load_dwordx4 v[48:51], v116, s[42:43]
	v_lshl_add_u64 v[22:23], s[42:43], 0, v[116:117]
	v_mov_b32_e32 v73, 0
	v_mov_b32_e32 v75, 0
	s_and_saveexec_b64 s[44:45], s[10:11]
	s_cbranch_execz .LBB0_1047
	global_load_dword v230, v[22:23], off offset:-4
.LBB0_1047:
	s_or_b64 exec, exec, s[44:45]
	s_and_saveexec_b64 s[44:45], s[4:5]
	s_cbranch_execz .LBB0_1049
	global_load_dword v231, v[22:23], off offset:16
.LBB0_1049:
	s_or_b64 exec, exec, s[44:45]
	s_or_b32 s46, s40, 1
	s_ashr_i32 s47, s46, 31
	s_lshl_b64 s[44:45], s[46:47], 17
	s_add_u32 s21, s58, s44
	s_addc_u32 s23, s59, s45
	s_add_u32 s44, s21, s73
	s_addc_u32 s45, s23, 0
	global_load_dwordx4 v[52:55], v116, s[44:45]
	v_lshl_add_u64 v[22:23], s[44:45], 0, v[116:117]
	v_mov_b32_e32 v77, 0
	v_mov_b32_e32 v79, 0
	s_and_saveexec_b64 s[48:49], s[10:11]
	s_cbranch_execz .LBB0_1051
	global_load_dword v232, v[22:23], off offset:-4
.LBB0_1051:
	s_or_b64 exec, exec, s[48:49]
	s_and_saveexec_b64 s[48:49], s[4:5]
	s_cbranch_execz .LBB0_1053
	global_load_dword v233, v[22:23], off offset:16
.LBB0_1053:
	s_or_b64 exec, exec, s[48:49]
	v_lshlrev_b32_e32 v84, 2, v118
	global_load_dword v72, v84, s[42:43] offset:12
	global_load_dwordx4 v[56:59], v84, s[42:43] offset:-4
	v_mov_b32_e32 v83, 0
	v_mov_b32_e32 v81, 0
	s_and_saveexec_b64 s[48:49], s[6:7]
	s_cbranch_execz .LBB0_1055
	v_mov_b32_e32 v85, v117
	v_lshl_add_u64 v[22:23], s[42:43], 0, v[84:85]
	global_load_dword v234, v[22:23], off offset:16
.LBB0_1055:
	s_or_b64 exec, exec, s[48:49]
	global_load_dword v74, v84, s[44:45] offset:12
	global_load_dwordx4 v[60:63], v84, s[44:45] offset:-4
	s_and_saveexec_b64 s[42:43], s[6:7]
	s_cbranch_execz .LBB0_1057
	v_mov_b32_e32 v85, v117
	v_lshl_add_u64 v[22:23], s[44:45], 0, v[84:85]
	global_load_dword v235, v[22:23], off offset:16

; __device__ __forceinline__ float bf_lo(unsigned w) { return __uint_as_float(w << 16); }
; __device__ __forceinline__ float bf_hi(unsigned w) { return __uint_as_float(w & 0xffff0000u); }
; __device__ __forceinline__ void conv8(const unsigned* zp, int cidx, float w0, float w1, float w2, float cb, float (&o)[8]) {
;     const u32x4 cur = *(const u32x4*)(zp + 4 * cidx); const unsigned prev = cidx > 0 ? zp[4 * cidx - 1] : 0u; const unsigned next = cidx < SEQ / 8 - 1 ? zp[4 * cidx + 4] : 0u;
;     const float zz[10] = {bf_hi(prev), bf_lo(cur.x), bf_hi(cur.x), bf_lo(cur.y), bf_hi(cur.y), bf_lo(cur.z), bf_hi(cur.z), bf_lo(cur.w), bf_hi(cur.w), bf_lo(next)};
; __device__ __forceinline__ void hyena_phase(LAS unsigned char* L, const Args& a, int vcu, int G) {
;     ...
;         fft_pass16<true, 10, true>(z, Thi, Tlo, tid);
.LBB0_1083:
	s_waitcnt vmcnt(0)
	s_and_saveexec_b64 s[74:75], s[10:11]
	v_and_b32_e32 v75, 0xffff0000, v230
	v_and_b32_e32 v79, 0xffff0000, v232
	s_mov_b64 exec, s[74:75]
	s_and_saveexec_b64 s[74:75], s[4:5]
	v_lshlrev_b32_e32 v73, 16, v231
	v_lshlrev_b32_e32 v77, 16, v233
	s_mov_b64 exec, s[74:75]
	s_and_saveexec_b64 s[74:75], s[6:7]
	v_lshlrev_b32_e32 v81, 16, v234
	v_lshlrev_b32_e32 v83, 16, v235
	s_mov_b64 exec, s[74:75]
	s_lshl_b64 s[44:45], s[40:41], 16
	s_lshl_b64 s[40:41], s[46:47], 16
	s_mov_b32 s52, 0
	s_mov_b64 s[46:47], -1
